# P2b gelu pre-pass: bias loaded once before the loop, per-row-group counted vmcnt waits instead of a drain after every store
# speedup vs baseline: 1.0051x; 1.0032x over previous
.LBB0_711:
	s_lshl_b32 s4, s9, 8
	s_ashr_i32 s3, s2, 31
	s_ashr_i32 s5, s4, 31
	s_lshl_b64 s[10:11], s[2:3], 17
	s_lshl_b32 s6, s2, 8
	v_lshl_add_u64 v[142:143], s[4:5], 2, v[130:131]
	v_lshl_add_u64 v[144:145], v[134:135], 0, s[10:11]
	v_lshl_add_u64 v[146:147], v[136:137], 0, s[10:11]
	v_lshl_add_u64 v[148:149], v[138:139], 0, s[10:11]
	v_lshl_add_u64 v[150:151], v[140:141], 0, s[10:11]
	s_mov_b64 s[4:5], 0
	v_mov_b32_e32 v157, v152
	v_mov_b32_e32 v158, v156
	v_mov_b32_e32 v159, v155
	v_mov_b32_e32 v162, v154
	v_mov_b32_e32 v163, v153
	v_mov_b32_e32 v164, v161
	global_load_dwordx4 v[166:169], v[142:143], off offset:16
	global_load_dwordx4 v[170:173], v[142:143], off
.LBB0_712:
	v_and_b32_e32 v0, 0xf8, v157
	v_lshlrev_b32_e32 v128, 2, v0
	v_add_u32_e32 v0, s6, v164
	v_ashrrev_i32_e32 v1, 31, v0
	v_lshl_add_u64 v[20:21], s[82:83], 0, v[128:129]
	v_lshlrev_b64 v[2:3], 10, v[0:1]
	v_lshl_add_u64 v[2:3], v[20:21], 0, v[2:3]
	global_load_dwordx4 v[96:99], v[2:3], off offset:16
	global_load_dwordx4 v[104:107], v[2:3], off
	v_add_u32_e32 v2, 0x2000, v0
	v_ashrrev_i32_e32 v3, 31, v2
	v_lshlrev_b64 v[2:3], 10, v[2:3]
	v_lshl_add_u64 v[2:3], v[20:21], 0, v[2:3]
	global_load_dwordx4 v[100:103], v[2:3], off offset:16
	global_load_dwordx4 v[112:115], v[2:3], off
	v_add_u32_e32 v2, 0x4000, v0
	v_add_u32_e32 v0, 0x6000, v0
	v_ashrrev_i32_e32 v3, 31, v2
	v_ashrrev_i32_e32 v1, 31, v0
	v_lshlrev_b64 v[2:3], 10, v[2:3]
	v_lshlrev_b64 v[0:1], 10, v[0:1]
	v_lshl_add_u64 v[2:3], v[20:21], 0, v[2:3]
	v_lshl_add_u64 v[0:1], v[20:21], 0, v[0:1]
	global_load_dwordx4 v[108:111], v[2:3], off offset:16
	global_load_dwordx4 v[120:123], v[2:3], off
	global_load_dwordx4 v[116:119], v[0:1], off offset:16
	global_load_dwordx4 v[124:127], v[0:1], off
	v_add_u32_e32 v0, s6, v159
	v_ashrrev_i32_e32 v1, 31, v0
	v_lshlrev_b64 v[2:3], 10, v[0:1]
	v_lshl_add_u64 v[2:3], v[20:21], 0, v[2:3]
	global_load_dwordx4 v[64:67], v[2:3], off offset:16
	global_load_dwordx4 v[72:75], v[2:3], off
	v_add_u32_e32 v2, 0x2000, v0
	v_ashrrev_i32_e32 v3, 31, v2
	v_lshlrev_b64 v[2:3], 10, v[2:3]
	v_lshl_add_u64 v[2:3], v[20:21], 0, v[2:3]
	global_load_dwordx4 v[68:71], v[2:3], off offset:16
	global_load_dwordx4 v[80:83], v[2:3], off
	v_add_u32_e32 v2, 0x4000, v0
	v_add_u32_e32 v0, 0x6000, v0
	v_ashrrev_i32_e32 v3, 31, v2
	v_ashrrev_i32_e32 v1, 31, v0
	v_lshlrev_b64 v[2:3], 10, v[2:3]
	v_lshlrev_b64 v[0:1], 10, v[0:1]
	v_lshl_add_u64 v[2:3], v[20:21], 0, v[2:3]
	v_lshl_add_u64 v[0:1], v[20:21], 0, v[0:1]
	global_load_dwordx4 v[76:79], v[2:3], off offset:16
	global_load_dwordx4 v[88:91], v[2:3], off
	global_load_dwordx4 v[84:87], v[0:1], off offset:16
	global_load_dwordx4 v[92:95], v[0:1], off
	v_add_u32_e32 v0, s6, v162
	v_ashrrev_i32_e32 v1, 31, v0
	v_lshlrev_b64 v[2:3], 10, v[0:1]
	v_lshl_add_u64 v[2:3], v[20:21], 0, v[2:3]
	global_load_dwordx4 v[32:35], v[2:3], off offset:16
	global_load_dwordx4 v[40:43], v[2:3], off
	v_add_u32_e32 v2, 0x2000, v0
	v_ashrrev_i32_e32 v3, 31, v2
	v_lshlrev_b64 v[2:3], 10, v[2:3]
	v_lshl_add_u64 v[2:3], v[20:21], 0, v[2:3]
	global_load_dwordx4 v[36:39], v[2:3], off offset:16
	global_load_dwordx4 v[48:51], v[2:3], off
	v_add_u32_e32 v2, 0x4000, v0
	v_add_u32_e32 v0, 0x6000, v0
	v_ashrrev_i32_e32 v3, 31, v2
	v_ashrrev_i32_e32 v1, 31, v0
	v_lshlrev_b64 v[2:3], 10, v[2:3]
	v_lshlrev_b64 v[0:1], 10, v[0:1]
	v_add_u32_e32 v22, s6, v163
	v_lshl_add_u64 v[2:3], v[20:21], 0, v[2:3]
	v_lshl_add_u64 v[0:1], v[20:21], 0, v[0:1]
	v_ashrrev_i32_e32 v23, 31, v22
	global_load_dwordx4 v[44:47], v[2:3], off offset:16
	global_load_dwordx4 v[56:59], v[2:3], off
	global_load_dwordx4 v[52:55], v[0:1], off offset:16
	global_load_dwordx4 v[60:63], v[0:1], off
	v_lshlrev_b64 v[0:1], 10, v[22:23]
	v_lshl_add_u64 v[4:5], v[20:21], 0, v[0:1]
	global_load_dwordx4 v[0:3], v[4:5], off offset:16
	global_load_dwordx4 v[8:11], v[4:5], off
	v_add_u32_e32 v4, 0x2000, v22
	v_ashrrev_i32_e32 v5, 31, v4
	v_lshlrev_b64 v[4:5], 10, v[4:5]
	v_lshl_add_u64 v[12:13], v[20:21], 0, v[4:5]
	global_load_dwordx4 v[4:7], v[12:13], off offset:16
	global_load_dwordx4 v[16:19], v[12:13], off
	v_add_u32_e32 v12, 0x4000, v22
	v_add_u32_e32 v22, 0x6000, v22
	v_ashrrev_i32_e32 v13, 31, v12
	v_ashrrev_i32_e32 v23, 31, v22
	v_lshlrev_b64 v[12:13], 10, v[12:13]
	v_lshlrev_b64 v[22:23], 10, v[22:23]
	v_lshl_add_u64 v[24:25], v[20:21], 0, v[12:13]
	v_lshl_add_u64 v[28:29], v[20:21], 0, v[22:23]
	global_load_dwordx4 v[12:15], v[24:25], off offset:16
	s_nop 0
	global_load_dwordx4 v[24:27], v[24:25], off
	s_nop 0
	global_load_dwordx4 v[20:23], v[28:29], off offset:16
	s_nop 0
	global_load_dwordx4 v[28:31], v[28:29], off
	s_nop 0
	v_add_u32_e32 v158, 0x800, v158
	s_movk_i32 s3, 0x17ff
	v_add_u32_e32 v164, 64, v164
	v_add_u32_e32 v163, 64, v163
	v_add_u32_e32 v162, 64, v162
	v_add_u32_e32 v159, 64, v159
	v_add_u32_e32 v157, 0x4000, v157
	s_waitcnt vmcnt(24)
	v_pk_add_f32 v[96:97], v[166:167], v[96:97]
	s_nop 0
	v_pk_add_f32 v[96:97], v[96:97], v[100:101]
	v_pk_add_f32 v[104:105], v[170:171], v[104:105]
	v_pk_add_f32 v[96:97], v[96:97], v[108:109]
	v_pk_add_f32 v[98:99], v[168:169], v[98:99]
	v_pk_add_f32 v[104:105], v[104:105], v[112:113]
	v_pk_add_f32 v[96:97], v[96:97], v[116:117]
	v_pk_add_f32 v[98:99], v[98:99], v[102:103]
	v_pk_add_f32 v[102:103], v[104:105], v[120:121]
	v_mul_f32_e32 v105, 0x3d372713, v96
	v_mul_f32_e32 v105, v96, v105
	v_fma_f32 v105, v96, v105, v96
	v_mul_f32_e32 v105, 0x3f4c422a, v105
	v_pk_add_f32 v[106:107], v[172:173], v[106:107]
	v_add_f32_e32 v105, v105, v105
	v_pk_add_f32 v[106:107], v[106:107], v[114:115]
	v_pk_add_f32 v[102:103], v[102:103], v[124:125]
	v_mul_f32_e32 v105, 0x3fb8aa3b, v105
	v_pk_add_f32 v[100:101], v[106:107], v[122:123]
	v_mul_f32_e32 v104, 0x3d372713, v102
	v_exp_f32_e32 v106, v105
	v_mul_f32_e32 v105, 0x3d372713, v103
	v_mul_f32_e32 v104, v102, v104
	v_mul_f32_e32 v105, v103, v105
	v_fma_f32 v104, v102, v104, v102
	v_fma_f32 v105, v103, v105, v103
	v_mul_f32_e32 v104, 0x3f4c422a, v104
	v_mul_f32_e32 v105, 0x3f4c422a, v105
	v_add_f32_e32 v104, v104, v104
	v_add_f32_e32 v105, v105, v105
	v_mul_f32_e32 v104, 0x3fb8aa3b, v104
	v_mul_f32_e32 v105, 0x3fb8aa3b, v105
	v_exp_f32_e32 v104, v104
	v_exp_f32_e32 v105, v105
	v_pk_add_f32 v[98:99], v[98:99], v[110:111]
	v_pk_mul_f32 v[102:103], v[102:103], 0.5 op_sel_hi:[1,0]
	v_pk_add_f32 v[98:99], v[98:99], v[118:119]
	v_pk_add_f32 v[104:105], v[104:105], 1.0 op_sel_hi:[1,0]
	v_pk_add_f32 v[100:101], v[100:101], v[126:127]
	v_div_scale_f32 v107, s[10:11], v105, v105, 2.0
	v_rcp_f32_e32 v108, v107
	s_nop 0
	v_fma_f32 v109, -v107, v108, 1.0
	v_fmac_f32_e32 v108, v109, v108
	v_div_scale_f32 v109, vcc, 2.0, v105, 2.0
	v_mul_f32_e32 v110, v109, v108
	v_fma_f32 v111, -v107, v110, v109
	v_fmac_f32_e32 v110, v111, v108
	v_fma_f32 v107, -v107, v110, v109
	v_div_fmas_f32 v107, v107, v108, v110
	v_div_fixup_f32 v105, v107, v105, 2.0
	v_div_scale_f32 v107, s[10:11], v104, v104, 2.0
	v_rcp_f32_e32 v108, v107
	s_nop 0
	v_fma_f32 v109, -v107, v108, 1.0
	v_fmac_f32_e32 v108, v109, v108
	v_div_scale_f32 v109, vcc, 2.0, v104, 2.0
	v_mul_f32_e32 v110, v109, v108
	v_fma_f32 v111, -v107, v110, v109
	v_fmac_f32_e32 v110, v111, v108
	v_fma_f32 v107, -v107, v110, v109
	v_div_fmas_f32 v107, v107, v108, v110
	v_div_fixup_f32 v104, v107, v104, 2.0
	v_pk_add_f32 v[104:105], v[104:105], 1.0 op_sel_hi:[1,0] neg_lo:[1,0] neg_hi:[1,0]
	s_nop 0
	v_pk_add_f32 v[104:105], v[104:105], 1.0 op_sel_hi:[1,0]
	s_nop 0
	v_pk_mul_f32 v[102:103], v[102:103], v[104:105]
	v_mul_f32_e32 v104, 0x3d372713, v97
	v_mul_f32_e32 v104, v97, v104
	v_fma_f32 v104, v97, v104, v97
	v_mul_f32_e32 v104, 0x3f4c422a, v104
	v_add_f32_e32 v104, v104, v104
	v_mul_f32_e32 v104, 0x3fb8aa3b, v104
	v_exp_f32_e32 v107, v104
	v_pk_mul_f32 v[96:97], v[96:97], 0.5 op_sel_hi:[1,0]
	v_pk_add_f32 v[104:105], v[106:107], 1.0 op_sel_hi:[1,0]
	s_nop 0
	v_div_scale_f32 v106, s[10:11], v105, v105, 2.0
	v_rcp_f32_e32 v107, v106
	s_nop 0
	v_fma_f32 v108, -v106, v107, 1.0
	v_fmac_f32_e32 v107, v108, v107
	v_div_scale_f32 v108, vcc, 2.0, v105, 2.0
	v_mul_f32_e32 v109, v108, v107
	v_fma_f32 v110, -v106, v109, v108
	v_fmac_f32_e32 v109, v110, v107
	v_fma_f32 v106, -v106, v109, v108
	v_div_fmas_f32 v106, v106, v107, v109
	v_div_fixup_f32 v105, v106, v105, 2.0
	v_div_scale_f32 v106, s[10:11], v104, v104, 2.0
	v_rcp_f32_e32 v107, v106
	s_nop 0
	v_fma_f32 v108, -v106, v107, 1.0
	v_fmac_f32_e32 v107, v108, v107
	v_div_scale_f32 v108, vcc, 2.0, v104, 2.0
	v_mul_f32_e32 v109, v108, v107
	v_fma_f32 v110, -v106, v109, v108
	v_fmac_f32_e32 v109, v110, v107
	v_fma_f32 v106, -v106, v109, v108
	v_div_fmas_f32 v106, v106, v107, v109
	v_div_fixup_f32 v104, v106, v104, 2.0
	v_pk_add_f32 v[104:105], v[104:105], 1.0 op_sel_hi:[1,0] neg_lo:[1,0] neg_hi:[1,0]
	s_nop 0
	v_pk_add_f32 v[104:105], v[104:105], 1.0 op_sel_hi:[1,0]
	s_nop 0
	v_pk_mul_f32 v[104:105], v[96:97], v[104:105]
	v_mul_f32_e32 v97, 0x3d372713, v98
	v_mul_f32_e32 v97, v98, v97
	v_fma_f32 v97, v98, v97, v98
	v_mul_f32_e32 v97, 0x3f4c422a, v97
	v_add_f32_e32 v97, v97, v97
	v_mul_f32_e32 v97, 0x3fb8aa3b, v97
	v_mul_f32_e32 v96, 0x3d372713, v100
	v_exp_f32_e32 v106, v97
	v_mul_f32_e32 v97, 0x3d372713, v101
	v_mul_f32_e32 v96, v100, v96
	v_mul_f32_e32 v97, v101, v97
	v_fma_f32 v96, v100, v96, v100
	v_fma_f32 v97, v101, v97, v101
	v_mul_f32_e32 v96, 0x3f4c422a, v96
	v_mul_f32_e32 v97, 0x3f4c422a, v97
	v_add_f32_e32 v96, v96, v96
	v_add_f32_e32 v97, v97, v97
	v_mul_f32_e32 v96, 0x3fb8aa3b, v96
	v_mul_f32_e32 v97, 0x3fb8aa3b, v97
	v_exp_f32_e32 v96, v96
	v_exp_f32_e32 v97, v97
	v_pk_mul_f32 v[100:101], v[100:101], 0.5 op_sel_hi:[1,0]
	v_pk_add_f32 v[96:97], v[96:97], 1.0 op_sel_hi:[1,0]
	s_nop 0
	v_div_scale_f32 v107, s[10:11], v97, v97, 2.0
	v_rcp_f32_e32 v108, v107
	s_nop 0
	v_fma_f32 v109, -v107, v108, 1.0
	v_fmac_f32_e32 v108, v109, v108
	v_div_scale_f32 v109, vcc, 2.0, v97, 2.0
	v_mul_f32_e32 v110, v109, v108
	v_fma_f32 v111, -v107, v110, v109
	v_fmac_f32_e32 v110, v111, v108
	v_fma_f32 v107, -v107, v110, v109
	v_div_fmas_f32 v107, v107, v108, v110
	v_div_fixup_f32 v97, v107, v97, 2.0
	v_div_scale_f32 v107, s[10:11], v96, v96, 2.0
	v_rcp_f32_e32 v108, v107
	s_nop 0
	v_fma_f32 v109, -v107, v108, 1.0
	v_fmac_f32_e32 v108, v109, v108
	v_div_scale_f32 v109, vcc, 2.0, v96, 2.0
	v_mul_f32_e32 v110, v109, v108
	v_fma_f32 v111, -v107, v110, v109
	v_fmac_f32_e32 v110, v111, v108
	v_fma_f32 v107, -v107, v110, v109
	v_div_fmas_f32 v107, v107, v108, v110
	v_div_fixup_f32 v96, v107, v96, 2.0
	v_pk_add_f32 v[96:97], v[96:97], 1.0 op_sel_hi:[1,0] neg_lo:[1,0] neg_hi:[1,0]
	s_nop 0
	v_pk_add_f32 v[96:97], v[96:97], 1.0 op_sel_hi:[1,0]
	s_nop 0
	v_pk_mul_f32 v[100:101], v[100:101], v[96:97]
	v_mul_f32_e32 v96, 0x3d372713, v99
	v_mul_f32_e32 v96, v99, v96
	v_fma_f32 v96, v99, v96, v99
	v_mul_f32_e32 v96, 0x3f4c422a, v96
	v_add_f32_e32 v96, v96, v96
	v_mul_f32_e32 v96, 0x3fb8aa3b, v96
	v_exp_f32_e32 v107, v96
	v_pk_mul_f32 v[98:99], v[98:99], 0.5 op_sel_hi:[1,0]
	v_pk_add_f32 v[96:97], v[106:107], 1.0 op_sel_hi:[1,0]
	s_nop 0
	v_div_scale_f32 v106, s[10:11], v97, v97, 2.0
	v_rcp_f32_e32 v107, v106
	s_nop 0
	v_fma_f32 v108, -v106, v107, 1.0
	v_fmac_f32_e32 v107, v108, v107
	v_div_scale_f32 v108, vcc, 2.0, v97, 2.0
	v_mul_f32_e32 v109, v108, v107
	v_fma_f32 v110, -v106, v109, v108
	v_fmac_f32_e32 v109, v110, v107
	v_fma_f32 v106, -v106, v109, v108
	v_div_fmas_f32 v106, v106, v107, v109
	v_div_fixup_f32 v97, v106, v97, 2.0
	v_div_scale_f32 v106, s[10:11], v96, v96, 2.0
	v_rcp_f32_e32 v107, v106
	s_nop 0
	v_fma_f32 v108, -v106, v107, 1.0
	v_fmac_f32_e32 v107, v108, v107
	v_div_scale_f32 v108, vcc, 2.0, v96, 2.0
	v_mul_f32_e32 v109, v108, v107
	v_fma_f32 v110, -v106, v109, v108
	v_fmac_f32_e32 v109, v110, v107
	v_fma_f32 v106, -v106, v109, v108
	v_div_fmas_f32 v106, v106, v107, v109
	v_div_fixup_f32 v96, v106, v96, 2.0
	v_pk_add_f32 v[96:97], v[96:97], 1.0 op_sel_hi:[1,0] neg_lo:[1,0] neg_hi:[1,0]
	s_nop 0
	v_pk_add_f32 v[96:97], v[96:97], 1.0 op_sel_hi:[1,0]
	s_nop 0
	v_pk_mul_f32 v[106:107], v[98:99], v[96:97]
	v_cvt_pk_bf16_f32 v96, v102, v103
	v_cvt_pk_bf16_f32 v97, v100, v101
	v_cvt_pk_bf16_f32 v98, v104, v105
	v_cvt_pk_bf16_f32 v99, v106, v107
	v_lshl_add_u64 v[100:101], v[150:151], 0, v[132:133]
	global_store_dwordx4 v[100:101], v[96:99], off
	s_nop 0
	v_lshl_add_u64 v[150:151], v[150:151], 0, s[0:1]
	s_waitcnt vmcnt(17)
	v_pk_add_f32 v[64:65], v[166:167], v[64:65]
	s_nop 0
	v_pk_add_f32 v[64:65], v[64:65], v[68:69]
	v_pk_add_f32 v[72:73], v[170:171], v[72:73]
	v_pk_add_f32 v[64:65], v[64:65], v[76:77]
	v_pk_add_f32 v[66:67], v[168:169], v[66:67]
	v_pk_add_f32 v[72:73], v[72:73], v[80:81]
	v_pk_add_f32 v[64:65], v[64:65], v[84:85]
	v_pk_add_f32 v[66:67], v[66:67], v[70:71]
	v_pk_add_f32 v[70:71], v[72:73], v[88:89]
	v_mul_f32_e32 v73, 0x3d372713, v64
	v_mul_f32_e32 v73, v64, v73
	v_fma_f32 v73, v64, v73, v64
	v_mul_f32_e32 v73, 0x3f4c422a, v73
	v_pk_add_f32 v[74:75], v[172:173], v[74:75]
	v_add_f32_e32 v73, v73, v73
	v_pk_add_f32 v[74:75], v[74:75], v[82:83]
	v_pk_add_f32 v[70:71], v[70:71], v[92:93]
	v_mul_f32_e32 v73, 0x3fb8aa3b, v73
	v_pk_add_f32 v[68:69], v[74:75], v[90:91]
	v_mul_f32_e32 v72, 0x3d372713, v70
	v_exp_f32_e32 v74, v73
	v_mul_f32_e32 v73, 0x3d372713, v71
	v_mul_f32_e32 v72, v70, v72
	v_mul_f32_e32 v73, v71, v73
	v_fma_f32 v72, v70, v72, v70
	v_fma_f32 v73, v71, v73, v71
	v_mul_f32_e32 v72, 0x3f4c422a, v72
	v_mul_f32_e32 v73, 0x3f4c422a, v73
	v_add_f32_e32 v72, v72, v72
	v_add_f32_e32 v73, v73, v73
	v_mul_f32_e32 v72, 0x3fb8aa3b, v72
	v_mul_f32_e32 v73, 0x3fb8aa3b, v73
	v_exp_f32_e32 v72, v72
	v_exp_f32_e32 v73, v73
	v_pk_add_f32 v[66:67], v[66:67], v[78:79]
	v_pk_mul_f32 v[70:71], v[70:71], 0.5 op_sel_hi:[1,0]
	v_pk_add_f32 v[66:67], v[66:67], v[86:87]
	v_pk_add_f32 v[72:73], v[72:73], 1.0 op_sel_hi:[1,0]
	v_pk_add_f32 v[68:69], v[68:69], v[94:95]
	v_div_scale_f32 v75, s[10:11], v73, v73, 2.0
	v_rcp_f32_e32 v76, v75
	s_nop 0
	v_fma_f32 v77, -v75, v76, 1.0
	v_fmac_f32_e32 v76, v77, v76
	v_div_scale_f32 v77, vcc, 2.0, v73, 2.0
	v_mul_f32_e32 v78, v77, v76
	v_fma_f32 v79, -v75, v78, v77
	v_fmac_f32_e32 v78, v79, v76
	v_fma_f32 v75, -v75, v78, v77
	v_div_fmas_f32 v75, v75, v76, v78
	v_div_fixup_f32 v73, v75, v73, 2.0
	v_div_scale_f32 v75, s[10:11], v72, v72, 2.0
	v_rcp_f32_e32 v76, v75
	s_nop 0
	v_fma_f32 v77, -v75, v76, 1.0
	v_fmac_f32_e32 v76, v77, v76
	v_div_scale_f32 v77, vcc, 2.0, v72, 2.0
	v_mul_f32_e32 v78, v77, v76
	v_fma_f32 v79, -v75, v78, v77
	v_fmac_f32_e32 v78, v79, v76
	v_fma_f32 v75, -v75, v78, v77
	v_div_fmas_f32 v75, v75, v76, v78
	v_div_fixup_f32 v72, v75, v72, 2.0
	v_pk_add_f32 v[72:73], v[72:73], 1.0 op_sel_hi:[1,0] neg_lo:[1,0] neg_hi:[1,0]
	s_nop 0
	v_pk_add_f32 v[72:73], v[72:73], 1.0 op_sel_hi:[1,0]
	s_nop 0
	v_pk_mul_f32 v[70:71], v[70:71], v[72:73]
	v_mul_f32_e32 v72, 0x3d372713, v65
	v_mul_f32_e32 v72, v65, v72
	v_fma_f32 v72, v65, v72, v65
	v_mul_f32_e32 v72, 0x3f4c422a, v72
	v_add_f32_e32 v72, v72, v72
	v_mul_f32_e32 v72, 0x3fb8aa3b, v72
	v_exp_f32_e32 v75, v72
	v_pk_mul_f32 v[64:65], v[64:65], 0.5 op_sel_hi:[1,0]
	v_pk_add_f32 v[72:73], v[74:75], 1.0 op_sel_hi:[1,0]
	s_nop 0
	v_div_scale_f32 v74, s[10:11], v73, v73, 2.0
	v_rcp_f32_e32 v75, v74
	s_nop 0
	v_fma_f32 v76, -v74, v75, 1.0
	v_fmac_f32_e32 v75, v76, v75
	v_div_scale_f32 v76, vcc, 2.0, v73, 2.0
	v_mul_f32_e32 v77, v76, v75
	v_fma_f32 v78, -v74, v77, v76
	v_fmac_f32_e32 v77, v78, v75
	v_fma_f32 v74, -v74, v77, v76
	v_div_fmas_f32 v74, v74, v75, v77
	v_div_fixup_f32 v73, v74, v73, 2.0
	v_div_scale_f32 v74, s[10:11], v72, v72, 2.0
	v_rcp_f32_e32 v75, v74
	s_nop 0
	v_fma_f32 v76, -v74, v75, 1.0
	v_fmac_f32_e32 v75, v76, v75
	v_div_scale_f32 v76, vcc, 2.0, v72, 2.0
	v_mul_f32_e32 v77, v76, v75
	v_fma_f32 v78, -v74, v77, v76
	v_fmac_f32_e32 v77, v78, v75
	v_fma_f32 v74, -v74, v77, v76
	v_div_fmas_f32 v74, v74, v75, v77
	v_div_fixup_f32 v72, v74, v72, 2.0
	v_pk_add_f32 v[72:73], v[72:73], 1.0 op_sel_hi:[1,0] neg_lo:[1,0] neg_hi:[1,0]
	s_nop 0
	v_pk_add_f32 v[72:73], v[72:73], 1.0 op_sel_hi:[1,0]
	s_nop 0
	v_pk_mul_f32 v[72:73], v[64:65], v[72:73]
	v_mul_f32_e32 v65, 0x3d372713, v66
	v_mul_f32_e32 v65, v66, v65
	v_fma_f32 v65, v66, v65, v66
	v_mul_f32_e32 v65, 0x3f4c422a, v65
	v_add_f32_e32 v65, v65, v65
	v_mul_f32_e32 v65, 0x3fb8aa3b, v65
	v_mul_f32_e32 v64, 0x3d372713, v68
	v_exp_f32_e32 v74, v65
	v_mul_f32_e32 v65, 0x3d372713, v69
	v_mul_f32_e32 v64, v68, v64
	v_mul_f32_e32 v65, v69, v65
	v_fma_f32 v64, v68, v64, v68
	v_fma_f32 v65, v69, v65, v69
	v_mul_f32_e32 v64, 0x3f4c422a, v64
	v_mul_f32_e32 v65, 0x3f4c422a, v65
	v_add_f32_e32 v64, v64, v64
	v_add_f32_e32 v65, v65, v65
	v_mul_f32_e32 v64, 0x3fb8aa3b, v64
	v_mul_f32_e32 v65, 0x3fb8aa3b, v65
	v_exp_f32_e32 v64, v64
	v_exp_f32_e32 v65, v65
	v_pk_mul_f32 v[68:69], v[68:69], 0.5 op_sel_hi:[1,0]
	v_pk_add_f32 v[64:65], v[64:65], 1.0 op_sel_hi:[1,0]
	s_nop 0
	v_div_scale_f32 v75, s[10:11], v65, v65, 2.0
	v_rcp_f32_e32 v76, v75
	s_nop 0
	v_fma_f32 v77, -v75, v76, 1.0
	v_fmac_f32_e32 v76, v77, v76
	v_div_scale_f32 v77, vcc, 2.0, v65, 2.0
	v_mul_f32_e32 v78, v77, v76
	v_fma_f32 v79, -v75, v78, v77
	v_fmac_f32_e32 v78, v79, v76
	v_fma_f32 v75, -v75, v78, v77
	v_div_fmas_f32 v75, v75, v76, v78
	v_div_fixup_f32 v65, v75, v65, 2.0
	v_div_scale_f32 v75, s[10:11], v64, v64, 2.0
	v_rcp_f32_e32 v76, v75
	s_nop 0
	v_fma_f32 v77, -v75, v76, 1.0
	v_fmac_f32_e32 v76, v77, v76
	v_div_scale_f32 v77, vcc, 2.0, v64, 2.0
	v_mul_f32_e32 v78, v77, v76
	v_fma_f32 v79, -v75, v78, v77
	v_fmac_f32_e32 v78, v79, v76
	v_fma_f32 v75, -v75, v78, v77
	v_div_fmas_f32 v75, v75, v76, v78
	v_div_fixup_f32 v64, v75, v64, 2.0
	v_pk_add_f32 v[64:65], v[64:65], 1.0 op_sel_hi:[1,0] neg_lo:[1,0] neg_hi:[1,0]
	s_nop 0
	v_pk_add_f32 v[64:65], v[64:65], 1.0 op_sel_hi:[1,0]
	s_nop 0
	v_pk_mul_f32 v[68:69], v[68:69], v[64:65]
	v_mul_f32_e32 v64, 0x3d372713, v67
	v_mul_f32_e32 v64, v67, v64
	v_fma_f32 v64, v67, v64, v67
	v_mul_f32_e32 v64, 0x3f4c422a, v64
	v_add_f32_e32 v64, v64, v64
	v_mul_f32_e32 v64, 0x3fb8aa3b, v64
	v_exp_f32_e32 v75, v64
	v_pk_mul_f32 v[66:67], v[66:67], 0.5 op_sel_hi:[1,0]
	v_pk_add_f32 v[64:65], v[74:75], 1.0 op_sel_hi:[1,0]
	s_nop 0
	v_div_scale_f32 v74, s[10:11], v65, v65, 2.0
	v_rcp_f32_e32 v75, v74
	s_nop 0
	v_fma_f32 v76, -v74, v75, 1.0
	v_fmac_f32_e32 v75, v76, v75
	v_div_scale_f32 v76, vcc, 2.0, v65, 2.0
	v_mul_f32_e32 v77, v76, v75
	v_fma_f32 v78, -v74, v77, v76
	v_fmac_f32_e32 v77, v78, v75
	v_fma_f32 v74, -v74, v77, v76
	v_div_fmas_f32 v74, v74, v75, v77
	v_div_fixup_f32 v65, v74, v65, 2.0
	v_div_scale_f32 v74, s[10:11], v64, v64, 2.0
	v_rcp_f32_e32 v75, v74
	s_nop 0
	v_fma_f32 v76, -v74, v75, 1.0
	v_fmac_f32_e32 v75, v76, v75
	v_div_scale_f32 v76, vcc, 2.0, v64, 2.0
	v_mul_f32_e32 v77, v76, v75
	v_fma_f32 v78, -v74, v77, v76
	v_fmac_f32_e32 v77, v78, v75
	v_fma_f32 v74, -v74, v77, v76
	v_div_fmas_f32 v74, v74, v75, v77
	v_div_fixup_f32 v64, v74, v64, 2.0
	v_pk_add_f32 v[64:65], v[64:65], 1.0 op_sel_hi:[1,0] neg_lo:[1,0] neg_hi:[1,0]
	s_nop 0
	v_pk_add_f32 v[64:65], v[64:65], 1.0 op_sel_hi:[1,0]
	s_nop 0
	v_pk_mul_f32 v[74:75], v[66:67], v[64:65]
	v_cvt_pk_bf16_f32 v64, v70, v71
	v_cvt_pk_bf16_f32 v65, v68, v69
	v_cvt_pk_bf16_f32 v66, v72, v73
	v_cvt_pk_bf16_f32 v67, v74, v75
	v_lshl_add_u64 v[68:69], v[144:145], 0, v[132:133]
	global_store_dwordx4 v[68:69], v[64:67], off
	s_nop 0
	v_lshl_add_u64 v[144:145], v[144:145], 0, s[0:1]
	s_waitcnt vmcnt(10)
	v_pk_add_f32 v[32:33], v[166:167], v[32:33]
	s_nop 0
	v_pk_add_f32 v[32:33], v[32:33], v[36:37]
	v_pk_add_f32 v[40:41], v[170:171], v[40:41]
	v_pk_add_f32 v[32:33], v[32:33], v[44:45]
	v_pk_add_f32 v[34:35], v[168:169], v[34:35]
	v_pk_add_f32 v[40:41], v[40:41], v[48:49]
	v_pk_add_f32 v[32:33], v[32:33], v[52:53]
	v_pk_add_f32 v[34:35], v[34:35], v[38:39]
	v_pk_add_f32 v[38:39], v[40:41], v[56:57]
	v_mul_f32_e32 v41, 0x3d372713, v32
	v_mul_f32_e32 v41, v32, v41
	v_fma_f32 v41, v32, v41, v32
	v_mul_f32_e32 v41, 0x3f4c422a, v41
	v_pk_add_f32 v[42:43], v[172:173], v[42:43]
	v_add_f32_e32 v41, v41, v41
	v_pk_add_f32 v[42:43], v[42:43], v[50:51]
	v_pk_add_f32 v[38:39], v[38:39], v[60:61]
	v_mul_f32_e32 v41, 0x3fb8aa3b, v41
	v_pk_add_f32 v[36:37], v[42:43], v[58:59]
	v_mul_f32_e32 v40, 0x3d372713, v38
	v_exp_f32_e32 v42, v41
	v_mul_f32_e32 v41, 0x3d372713, v39
	v_mul_f32_e32 v40, v38, v40
	v_mul_f32_e32 v41, v39, v41
	v_fma_f32 v40, v38, v40, v38
	v_fma_f32 v41, v39, v41, v39
	v_mul_f32_e32 v40, 0x3f4c422a, v40
	v_mul_f32_e32 v41, 0x3f4c422a, v41
	v_add_f32_e32 v40, v40, v40
	v_add_f32_e32 v41, v41, v41
	v_mul_f32_e32 v40, 0x3fb8aa3b, v40
	v_mul_f32_e32 v41, 0x3fb8aa3b, v41
	v_exp_f32_e32 v40, v40
	v_exp_f32_e32 v41, v41
	v_pk_add_f32 v[34:35], v[34:35], v[46:47]
	v_pk_mul_f32 v[38:39], v[38:39], 0.5 op_sel_hi:[1,0]
	v_pk_add_f32 v[34:35], v[34:35], v[54:55]
	v_pk_add_f32 v[40:41], v[40:41], 1.0 op_sel_hi:[1,0]
	v_pk_add_f32 v[36:37], v[36:37], v[62:63]
	v_div_scale_f32 v43, s[10:11], v41, v41, 2.0
	v_rcp_f32_e32 v44, v43
	s_nop 0
	v_fma_f32 v45, -v43, v44, 1.0
	v_fmac_f32_e32 v44, v45, v44
	v_div_scale_f32 v45, vcc, 2.0, v41, 2.0
	v_mul_f32_e32 v46, v45, v44
	v_fma_f32 v47, -v43, v46, v45
	v_fmac_f32_e32 v46, v47, v44
	v_fma_f32 v43, -v43, v46, v45
	v_div_fmas_f32 v43, v43, v44, v46
	v_div_fixup_f32 v41, v43, v41, 2.0
	v_div_scale_f32 v43, s[10:11], v40, v40, 2.0
	v_rcp_f32_e32 v44, v43
	s_nop 0
	v_fma_f32 v45, -v43, v44, 1.0
	v_fmac_f32_e32 v44, v45, v44
	v_div_scale_f32 v45, vcc, 2.0, v40, 2.0
	v_mul_f32_e32 v46, v45, v44
	v_fma_f32 v47, -v43, v46, v45
	v_fmac_f32_e32 v46, v47, v44
	v_fma_f32 v43, -v43, v46, v45
	v_div_fmas_f32 v43, v43, v44, v46
	v_div_fixup_f32 v40, v43, v40, 2.0
	v_pk_add_f32 v[40:41], v[40:41], 1.0 op_sel_hi:[1,0] neg_lo:[1,0] neg_hi:[1,0]
	s_nop 0
	v_pk_add_f32 v[40:41], v[40:41], 1.0 op_sel_hi:[1,0]
	s_nop 0
	v_pk_mul_f32 v[38:39], v[38:39], v[40:41]
	v_mul_f32_e32 v40, 0x3d372713, v33
	v_mul_f32_e32 v40, v33, v40
	v_fma_f32 v40, v33, v40, v33
	v_mul_f32_e32 v40, 0x3f4c422a, v40
	v_add_f32_e32 v40, v40, v40
	v_mul_f32_e32 v40, 0x3fb8aa3b, v40
	v_exp_f32_e32 v43, v40
	v_pk_mul_f32 v[32:33], v[32:33], 0.5 op_sel_hi:[1,0]
	v_pk_add_f32 v[40:41], v[42:43], 1.0 op_sel_hi:[1,0]
	s_nop 0
	v_div_scale_f32 v42, s[10:11], v41, v41, 2.0
	v_rcp_f32_e32 v43, v42
	s_nop 0
	v_fma_f32 v44, -v42, v43, 1.0
	v_fmac_f32_e32 v43, v44, v43
	v_div_scale_f32 v44, vcc, 2.0, v41, 2.0
	v_mul_f32_e32 v45, v44, v43
	v_fma_f32 v46, -v42, v45, v44
	v_fmac_f32_e32 v45, v46, v43
	v_fma_f32 v42, -v42, v45, v44
	v_div_fmas_f32 v42, v42, v43, v45
	v_div_fixup_f32 v41, v42, v41, 2.0
	v_div_scale_f32 v42, s[10:11], v40, v40, 2.0
	v_rcp_f32_e32 v43, v42
	s_nop 0
	v_fma_f32 v44, -v42, v43, 1.0
	v_fmac_f32_e32 v43, v44, v43
	v_div_scale_f32 v44, vcc, 2.0, v40, 2.0
	v_mul_f32_e32 v45, v44, v43
	v_fma_f32 v46, -v42, v45, v44
	v_fmac_f32_e32 v45, v46, v43
	v_fma_f32 v42, -v42, v45, v44
	v_div_fmas_f32 v42, v42, v43, v45
	v_div_fixup_f32 v40, v42, v40, 2.0
	v_pk_add_f32 v[40:41], v[40:41], 1.0 op_sel_hi:[1,0] neg_lo:[1,0] neg_hi:[1,0]
	s_nop 0
	v_pk_add_f32 v[40:41], v[40:41], 1.0 op_sel_hi:[1,0]
	s_nop 0
	v_pk_mul_f32 v[40:41], v[32:33], v[40:41]
	v_mul_f32_e32 v33, 0x3d372713, v34
	v_mul_f32_e32 v33, v34, v33
	v_fma_f32 v33, v34, v33, v34
	v_mul_f32_e32 v33, 0x3f4c422a, v33
	v_add_f32_e32 v33, v33, v33
	v_mul_f32_e32 v33, 0x3fb8aa3b, v33
	v_mul_f32_e32 v32, 0x3d372713, v36
	v_exp_f32_e32 v42, v33
	v_mul_f32_e32 v33, 0x3d372713, v37
	v_mul_f32_e32 v32, v36, v32
	v_mul_f32_e32 v33, v37, v33
	v_fma_f32 v32, v36, v32, v36
	v_fma_f32 v33, v37, v33, v37
	v_mul_f32_e32 v32, 0x3f4c422a, v32
	v_mul_f32_e32 v33, 0x3f4c422a, v33
	v_add_f32_e32 v32, v32, v32
	v_add_f32_e32 v33, v33, v33
	v_mul_f32_e32 v32, 0x3fb8aa3b, v32
	v_mul_f32_e32 v33, 0x3fb8aa3b, v33
	v_exp_f32_e32 v32, v32
	v_exp_f32_e32 v33, v33
	v_pk_mul_f32 v[36:37], v[36:37], 0.5 op_sel_hi:[1,0]
	v_pk_add_f32 v[32:33], v[32:33], 1.0 op_sel_hi:[1,0]
	s_nop 0
	v_div_scale_f32 v43, s[10:11], v33, v33, 2.0
	v_rcp_f32_e32 v44, v43
	s_nop 0
	v_fma_f32 v45, -v43, v44, 1.0
	v_fmac_f32_e32 v44, v45, v44
	v_div_scale_f32 v45, vcc, 2.0, v33, 2.0
	v_mul_f32_e32 v46, v45, v44
	v_fma_f32 v47, -v43, v46, v45
	v_fmac_f32_e32 v46, v47, v44
	v_fma_f32 v43, -v43, v46, v45
	v_div_fmas_f32 v43, v43, v44, v46
	v_div_fixup_f32 v33, v43, v33, 2.0
	v_div_scale_f32 v43, s[10:11], v32, v32, 2.0
	v_rcp_f32_e32 v44, v43
	s_nop 0
	v_fma_f32 v45, -v43, v44, 1.0
	v_fmac_f32_e32 v44, v45, v44
	v_div_scale_f32 v45, vcc, 2.0, v32, 2.0
	v_mul_f32_e32 v46, v45, v44
	v_fma_f32 v47, -v43, v46, v45
	v_fmac_f32_e32 v46, v47, v44
	v_fma_f32 v43, -v43, v46, v45
	v_div_fmas_f32 v43, v43, v44, v46
	v_div_fixup_f32 v32, v43, v32, 2.0
	v_pk_add_f32 v[32:33], v[32:33], 1.0 op_sel_hi:[1,0] neg_lo:[1,0] neg_hi:[1,0]
	s_nop 0
	v_pk_add_f32 v[32:33], v[32:33], 1.0 op_sel_hi:[1,0]
	s_nop 0
	v_pk_mul_f32 v[36:37], v[36:37], v[32:33]
	v_mul_f32_e32 v32, 0x3d372713, v35
	v_mul_f32_e32 v32, v35, v32
	v_fma_f32 v32, v35, v32, v35
	v_mul_f32_e32 v32, 0x3f4c422a, v32
	v_add_f32_e32 v32, v32, v32
	v_mul_f32_e32 v32, 0x3fb8aa3b, v32
	v_exp_f32_e32 v43, v32
	v_pk_mul_f32 v[34:35], v[34:35], 0.5 op_sel_hi:[1,0]
	v_pk_add_f32 v[32:33], v[42:43], 1.0 op_sel_hi:[1,0]
	s_nop 0
	v_div_scale_f32 v42, s[10:11], v33, v33, 2.0
	v_rcp_f32_e32 v43, v42
	s_nop 0
	v_fma_f32 v44, -v42, v43, 1.0
	v_fmac_f32_e32 v43, v44, v43
	v_div_scale_f32 v44, vcc, 2.0, v33, 2.0
	v_mul_f32_e32 v45, v44, v43
	v_fma_f32 v46, -v42, v45, v44
	v_fmac_f32_e32 v45, v46, v43
	v_fma_f32 v42, -v42, v45, v44
	v_div_fmas_f32 v42, v42, v43, v45
	v_div_fixup_f32 v33, v42, v33, 2.0
	v_div_scale_f32 v42, s[10:11], v32, v32, 2.0
	v_rcp_f32_e32 v43, v42
	s_nop 0
	v_fma_f32 v44, -v42, v43, 1.0
	v_fmac_f32_e32 v43, v44, v43
	v_div_scale_f32 v44, vcc, 2.0, v32, 2.0
	v_mul_f32_e32 v45, v44, v43
	v_fma_f32 v46, -v42, v45, v44
	v_fmac_f32_e32 v45, v46, v43
	v_fma_f32 v42, -v42, v45, v44
	v_div_fmas_f32 v42, v42, v43, v45
	v_div_fixup_f32 v32, v42, v32, 2.0
	v_pk_add_f32 v[32:33], v[32:33], 1.0 op_sel_hi:[1,0] neg_lo:[1,0] neg_hi:[1,0]
	s_nop 0
	v_pk_add_f32 v[32:33], v[32:33], 1.0 op_sel_hi:[1,0]
	s_nop 0
	v_pk_mul_f32 v[42:43], v[34:35], v[32:33]
	v_cvt_pk_bf16_f32 v32, v38, v39
	v_cvt_pk_bf16_f32 v33, v36, v37
	v_cvt_pk_bf16_f32 v34, v40, v41
	v_cvt_pk_bf16_f32 v35, v42, v43
	v_lshl_add_u64 v[36:37], v[146:147], 0, v[132:133]
	global_store_dwordx4 v[36:37], v[32:35], off
	s_nop 0
	v_lshl_add_u64 v[146:147], v[146:147], 0, s[0:1]
	s_waitcnt vmcnt(3)
	v_pk_add_f32 v[0:1], v[166:167], v[0:1]
	s_nop 0
	v_pk_add_f32 v[0:1], v[0:1], v[4:5]
	v_pk_add_f32 v[8:9], v[170:171], v[8:9]
	v_pk_add_f32 v[0:1], v[0:1], v[12:13]
	v_pk_add_f32 v[2:3], v[168:169], v[2:3]
	v_pk_add_f32 v[8:9], v[8:9], v[16:17]
	v_pk_add_f32 v[0:1], v[0:1], v[20:21]
	v_pk_add_f32 v[2:3], v[2:3], v[6:7]
	v_pk_add_f32 v[6:7], v[8:9], v[24:25]
	v_mul_f32_e32 v9, 0x3d372713, v0
	v_mul_f32_e32 v9, v0, v9
	v_fma_f32 v9, v0, v9, v0
	v_mul_f32_e32 v9, 0x3f4c422a, v9
	v_pk_add_f32 v[10:11], v[172:173], v[10:11]
	v_add_f32_e32 v9, v9, v9
	v_pk_add_f32 v[10:11], v[10:11], v[18:19]
	v_pk_add_f32 v[6:7], v[6:7], v[28:29]
	v_mul_f32_e32 v9, 0x3fb8aa3b, v9
	v_pk_add_f32 v[4:5], v[10:11], v[26:27]
	v_mul_f32_e32 v8, 0x3d372713, v6
	v_exp_f32_e32 v10, v9
	v_mul_f32_e32 v9, 0x3d372713, v7
	v_mul_f32_e32 v8, v6, v8
	v_mul_f32_e32 v9, v7, v9
	v_fma_f32 v8, v6, v8, v6
	v_fma_f32 v9, v7, v9, v7
	v_mul_f32_e32 v8, 0x3f4c422a, v8
	v_mul_f32_e32 v9, 0x3f4c422a, v9
	v_add_f32_e32 v8, v8, v8
	v_add_f32_e32 v9, v9, v9
	v_mul_f32_e32 v8, 0x3fb8aa3b, v8
	v_mul_f32_e32 v9, 0x3fb8aa3b, v9
	v_exp_f32_e32 v8, v8
	v_exp_f32_e32 v9, v9
	v_pk_add_f32 v[2:3], v[2:3], v[14:15]
	v_pk_mul_f32 v[6:7], v[6:7], 0.5 op_sel_hi:[1,0]
	v_pk_add_f32 v[2:3], v[2:3], v[22:23]
	v_pk_add_f32 v[8:9], v[8:9], 1.0 op_sel_hi:[1,0]
	v_pk_add_f32 v[4:5], v[4:5], v[30:31]
	v_div_scale_f32 v11, s[10:11], v9, v9, 2.0
	v_rcp_f32_e32 v12, v11
	s_nop 0
	v_fma_f32 v13, -v11, v12, 1.0
	v_fmac_f32_e32 v12, v13, v12
	v_div_scale_f32 v13, vcc, 2.0, v9, 2.0
	v_mul_f32_e32 v14, v13, v12
	v_fma_f32 v15, -v11, v14, v13
	v_fmac_f32_e32 v14, v15, v12
	v_fma_f32 v11, -v11, v14, v13
	v_div_fmas_f32 v11, v11, v12, v14
	v_div_fixup_f32 v9, v11, v9, 2.0
	v_div_scale_f32 v11, s[10:11], v8, v8, 2.0
	v_rcp_f32_e32 v12, v11
	s_nop 0
	v_fma_f32 v13, -v11, v12, 1.0
	v_fmac_f32_e32 v12, v13, v12
	v_div_scale_f32 v13, vcc, 2.0, v8, 2.0
	v_mul_f32_e32 v14, v13, v12
	v_fma_f32 v15, -v11, v14, v13
	v_fmac_f32_e32 v14, v15, v12
	v_fma_f32 v11, -v11, v14, v13
	v_div_fmas_f32 v11, v11, v12, v14
	v_div_fixup_f32 v8, v11, v8, 2.0
	v_pk_add_f32 v[8:9], v[8:9], 1.0 op_sel_hi:[1,0] neg_lo:[1,0] neg_hi:[1,0]
	s_nop 0
	v_pk_add_f32 v[8:9], v[8:9], 1.0 op_sel_hi:[1,0]
	s_nop 0
	v_pk_mul_f32 v[6:7], v[6:7], v[8:9]
	v_mul_f32_e32 v8, 0x3d372713, v1
	v_mul_f32_e32 v8, v1, v8
	v_fma_f32 v8, v1, v8, v1
	v_mul_f32_e32 v8, 0x3f4c422a, v8
	v_add_f32_e32 v8, v8, v8
	v_mul_f32_e32 v8, 0x3fb8aa3b, v8
	v_exp_f32_e32 v11, v8
	v_pk_mul_f32 v[0:1], v[0:1], 0.5 op_sel_hi:[1,0]
	v_pk_add_f32 v[8:9], v[10:11], 1.0 op_sel_hi:[1,0]
	s_nop 0
	v_div_scale_f32 v10, s[10:11], v9, v9, 2.0
	v_rcp_f32_e32 v11, v10
	s_nop 0
	v_fma_f32 v12, -v10, v11, 1.0
	v_fmac_f32_e32 v11, v12, v11
	v_div_scale_f32 v12, vcc, 2.0, v9, 2.0
	v_mul_f32_e32 v13, v12, v11
	v_fma_f32 v14, -v10, v13, v12
	v_fmac_f32_e32 v13, v14, v11
	v_fma_f32 v10, -v10, v13, v12
	v_div_fmas_f32 v10, v10, v11, v13
	v_div_fixup_f32 v9, v10, v9, 2.0
	v_div_scale_f32 v10, s[10:11], v8, v8, 2.0
	v_rcp_f32_e32 v11, v10
	s_nop 0
	v_fma_f32 v12, -v10, v11, 1.0
	v_fmac_f32_e32 v11, v12, v11
	v_div_scale_f32 v12, vcc, 2.0, v8, 2.0
	v_mul_f32_e32 v13, v12, v11
	v_fma_f32 v14, -v10, v13, v12
	v_fmac_f32_e32 v13, v14, v11
	v_fma_f32 v10, -v10, v13, v12
	v_div_fmas_f32 v10, v10, v11, v13
	v_div_fixup_f32 v8, v10, v8, 2.0
	v_pk_add_f32 v[8:9], v[8:9], 1.0 op_sel_hi:[1,0] neg_lo:[1,0] neg_hi:[1,0]
	s_nop 0
	v_pk_add_f32 v[8:9], v[8:9], 1.0 op_sel_hi:[1,0]
	s_nop 0
	v_pk_mul_f32 v[8:9], v[0:1], v[8:9]
	v_mul_f32_e32 v1, 0x3d372713, v2
	v_mul_f32_e32 v1, v2, v1
	v_fma_f32 v1, v2, v1, v2
	v_mul_f32_e32 v1, 0x3f4c422a, v1
	v_add_f32_e32 v1, v1, v1
	v_mul_f32_e32 v1, 0x3fb8aa3b, v1
	v_mul_f32_e32 v0, 0x3d372713, v4
	v_exp_f32_e32 v10, v1
	v_mul_f32_e32 v1, 0x3d372713, v5
	v_mul_f32_e32 v0, v4, v0
	v_mul_f32_e32 v1, v5, v1
	v_fma_f32 v0, v4, v0, v4
	v_fma_f32 v1, v5, v1, v5
	v_mul_f32_e32 v0, 0x3f4c422a, v0
	v_mul_f32_e32 v1, 0x3f4c422a, v1
	v_add_f32_e32 v0, v0, v0
	v_add_f32_e32 v1, v1, v1
	v_mul_f32_e32 v0, 0x3fb8aa3b, v0
	v_mul_f32_e32 v1, 0x3fb8aa3b, v1
	v_exp_f32_e32 v0, v0
	v_exp_f32_e32 v1, v1
	v_pk_mul_f32 v[4:5], v[4:5], 0.5 op_sel_hi:[1,0]
	v_pk_add_f32 v[0:1], v[0:1], 1.0 op_sel_hi:[1,0]
	s_nop 0
	v_div_scale_f32 v11, s[10:11], v1, v1, 2.0
	v_rcp_f32_e32 v12, v11
	s_nop 0
	v_fma_f32 v13, -v11, v12, 1.0
	v_fmac_f32_e32 v12, v13, v12
	v_div_scale_f32 v13, vcc, 2.0, v1, 2.0
	v_mul_f32_e32 v14, v13, v12
	v_fma_f32 v15, -v11, v14, v13
	v_fmac_f32_e32 v14, v15, v12
	v_fma_f32 v11, -v11, v14, v13
	v_div_fmas_f32 v11, v11, v12, v14
	v_div_fixup_f32 v1, v11, v1, 2.0
	v_div_scale_f32 v11, s[10:11], v0, v0, 2.0
	v_rcp_f32_e32 v12, v11
	s_nop 0
	v_fma_f32 v13, -v11, v12, 1.0
	v_fmac_f32_e32 v12, v13, v12
	v_div_scale_f32 v13, vcc, 2.0, v0, 2.0
	v_mul_f32_e32 v14, v13, v12
	v_fma_f32 v15, -v11, v14, v13
	v_fmac_f32_e32 v14, v15, v12
	v_fma_f32 v11, -v11, v14, v13
	v_div_fmas_f32 v11, v11, v12, v14
	v_div_fixup_f32 v0, v11, v0, 2.0
	v_pk_add_f32 v[0:1], v[0:1], 1.0 op_sel_hi:[1,0] neg_lo:[1,0] neg_hi:[1,0]
	s_nop 0
	v_pk_add_f32 v[0:1], v[0:1], 1.0 op_sel_hi:[1,0]
	s_nop 0
	v_pk_mul_f32 v[4:5], v[4:5], v[0:1]
	v_mul_f32_e32 v0, 0x3d372713, v3
	v_mul_f32_e32 v0, v3, v0
	v_fma_f32 v0, v3, v0, v3
	v_mul_f32_e32 v0, 0x3f4c422a, v0
	v_add_f32_e32 v0, v0, v0
	v_mul_f32_e32 v0, 0x3fb8aa3b, v0
	v_exp_f32_e32 v11, v0
	v_pk_mul_f32 v[2:3], v[2:3], 0.5 op_sel_hi:[1,0]
	v_pk_add_f32 v[0:1], v[10:11], 1.0 op_sel_hi:[1,0]
	s_nop 0
	v_div_scale_f32 v10, s[10:11], v1, v1, 2.0
	v_rcp_f32_e32 v11, v10
	s_nop 0
	v_fma_f32 v12, -v10, v11, 1.0
	v_fmac_f32_e32 v11, v12, v11
	v_div_scale_f32 v12, vcc, 2.0, v1, 2.0
	v_mul_f32_e32 v13, v12, v11
	v_fma_f32 v14, -v10, v13, v12
	v_fmac_f32_e32 v13, v14, v11
	v_fma_f32 v10, -v10, v13, v12
	v_div_fmas_f32 v10, v10, v11, v13
	v_div_fixup_f32 v1, v10, v1, 2.0
	v_div_scale_f32 v10, s[10:11], v0, v0, 2.0
	v_rcp_f32_e32 v11, v10
	s_nop 0
	v_fma_f32 v12, -v10, v11, 1.0
	v_fmac_f32_e32 v11, v12, v11
	v_div_scale_f32 v12, vcc, 2.0, v0, 2.0
	v_mul_f32_e32 v13, v12, v11
	v_fma_f32 v14, -v10, v13, v12
	v_fmac_f32_e32 v13, v14, v11
	v_fma_f32 v10, -v10, v13, v12
	v_div_fmas_f32 v10, v10, v11, v13
	v_div_fixup_f32 v0, v10, v0, 2.0
	v_pk_add_f32 v[0:1], v[0:1], 1.0 op_sel_hi:[1,0] neg_lo:[1,0] neg_hi:[1,0]
	v_cmp_lt_u32_e32 vcc, s3, v158
	v_pk_add_f32 v[0:1], v[0:1], 1.0 op_sel_hi:[1,0]
	s_or_b64 s[4:5], vcc, s[4:5]
	v_pk_mul_f32 v[10:11], v[2:3], v[0:1]
	v_cvt_pk_bf16_f32 v0, v6, v7
	v_cvt_pk_bf16_f32 v1, v4, v5
	v_cvt_pk_bf16_f32 v2, v8, v9
	v_cvt_pk_bf16_f32 v3, v10, v11
	v_lshl_add_u64 v[4:5], v[148:149], 0, v[132:133]
	v_lshl_add_u64 v[148:149], v[148:149], 0, s[0:1]
	global_store_dwordx4 v[4:5], v[0:3], off
	s_andn2_b64 exec, exec, s[4:5]
	s_cbranch_execnz .LBB0_712
	s_or_b64 exec, exec, s[4:5]
	s_add_i32 s8, s8, 1
	s_mov_b64 s[4:5], 0
	s_branch .LBB0_703
